# plus: merge bias loads hoisted, e_phase row loop double-buffered with scalar control
# speedup vs baseline: 1.0129x; 1.0020x over previous
;     __device__ __forceinline__ void operator()(const f32x4 (&acc)[2][2][4][2], const pg8::Unit& u, int tid, int wr, int wc, int fr, int fq) const {
;     ...
;             const int br = u.sub >> 1; const bool isg = !(u.sub & 1);
;             const int col0 = u.pn * 256 + wc * 32 + 8 * fq;
;             u32x4* pk = park + tid; asm volatile("" : "+v"(pk));
; #pragma unroll
;             for (int bj = 0; bj < 2; ++bj) {
;                 f32x4 b0 = (f32x4){0.f, 0.f, 0.f, 0.f}, b1 = b0;
;                 if (isg) { const float* bp = bgate + br * 1024 + col0 + bj * 128; b0 = *(const f32x4*)bp * -1.4426950408889634f; b1 = *(const f32x4*)(bp + 4) * -1.4426950408889634f; }
.LBB0_181:
	v_mov_b32_e32 v134, v183
	s_lshl_b32 s3, s34, 8
	v_readlane_b32 s4, v244, 34
	s_add_i32 s3, s3, s4
	v_and_b32_e32 v133, 15, v134
	v_bfe_u32 v0, v134, 4, 2
	v_or_b32_e32 v131, s3, v133
	s_cmp_lt_i32 s5, 1
	s_mov_b64 s[6:7], -1
	s_cbranch_scc1 .LBB0_287
	s_cmp_lg_u32 s5, 1
	s_cbranch_scc0 .LBB0_284
	s_ashr_i32 s6, s22, 1
	s_and_b32 s7, s22, 1
	s_cmp_eq_u32 s7, 0
	s_cselect_b64 s[96:97], -1, 0
	s_cmp_eq_u32 s7, 1
	s_cselect_b64 s[28:29], -1, 0
	s_lshl_b32 s7, s52, 8
	v_lshl_or_b32 v135, v0, 3, s7
	v_readlane_b32 s10, v244, 44
	v_or_b32_e32 v136, s53, v135
	v_ashrrev_i32_e32 v135, 31, v134
	v_readlane_b32 s11, v244, 45
	s_lshl_b32 s66, s6, 10
	v_ashrrev_i32_e32 v137, 31, v136
	v_lshl_add_u64 v[138:139], v[134:135], 4, s[10:11]
	s_ashr_i32 s67, s66, 31
	s_and_b64 vcc, exec, s[28:29]
	s_cbranch_vccnz .Lmerge_odd
	v_mov_b32_e32 v150, 0
	s_and_b64 vcc, exec, s[28:29]
	v_mov_b32_e32 v151, 0
	v_mov_b32_e32 v144, 0
	v_mov_b32_e32 v145, 0
	v_mov_b32_e32 v142, 0
	v_mov_b32_e32 v143, 0
	v_mov_b32_e32 v140, 0
	v_mov_b32_e32 v141, 0
	s_cbranch_vccnz .LBB0_185
	s_lshl_b64 s[10:11], s[66:67], 2
	v_readlane_b32 s14, v244, 46
	v_readlane_b32 s15, v244, 47
	s_add_u32 s10, s14, s10
	s_addc_u32 s11, s15, s11
	v_lshl_add_u64 v[144:145], v[136:137], 2, s[10:11]
	global_load_dwordx4 v[140:143], v[144:145], off
	global_load_dwordx4 v[152:155], v[144:145], off offset:16
	global_load_dwordx4 v[200:203], v[144:145], off offset:512
	global_load_dwordx4 v[204:207], v[144:145], off offset:528
	s_mov_b32 s10, 0xbfb8aa3b
	s_waitcnt vmcnt(0)
	v_pk_mul_f32 v[144:145], v[142:143], s[10:11] op_sel_hi:[1,0]
	v_pk_mul_f32 v[150:151], v[140:141], s[10:11] op_sel_hi:[1,0]
	v_pk_mul_f32 v[140:141], v[154:155], s[10:11] op_sel_hi:[1,0]
	v_pk_mul_f32 v[142:143], v[152:153], s[10:11] op_sel_hi:[1,0]

;     __device__ __forceinline__ void operator()(const f32x4 (&acc)[2][2][4][2], const pg8::Unit& u, int tid, int wr, int wc, int fr, int fq) const {
;     ...
;             for (int bj = 0; bj < 2; ++bj) {
;                 f32x4 b0 = (f32x4){0.f, 0.f, 0.f, 0.f}, b1 = b0;
;                 if (isg) { const float* bp = bgate + br * 1024 + col0 + bj * 128; b0 = *(const f32x4*)bp * -1.4426950408889634f; b1 = *(const f32x4*)(bp + 4) * -1.4426950408889634f; }
.LBB0_233:
	v_mov_b32_e32 v150, 0
	s_andn2_b64 vcc, exec, s[96:97]
	v_mov_b32_e32 v151, 0
	v_mov_b32_e32 v144, 0
	v_mov_b32_e32 v145, 0
	v_mov_b32_e32 v142, 0
	v_mov_b32_e32 v143, 0
	v_mov_b32_e32 v140, 0
	v_mov_b32_e32 v141, 0
	s_cbranch_vccnz .LBB0_235
	s_mov_b32 s6, 0xbfb8aa3b
	v_pk_mul_f32 v[144:145], v[202:203], s[6:7] op_sel_hi:[1,0]
	v_pk_mul_f32 v[150:151], v[200:201], s[6:7] op_sel_hi:[1,0]
	v_pk_mul_f32 v[140:141], v[206:207], s[6:7] op_sel_hi:[1,0]
	v_pk_mul_f32 v[142:143], v[204:205], s[6:7] op_sel_hi:[1,0]

; __device__ __forceinline__ float bflo(unsigned w) { return __uint_as_float(w << 16); }
; __device__ __forceinline__ float bfhi(unsigned w) { return __uint_as_float(w & 0xffff0000u); }
; __device__ __forceinline__ void e_phase(const Ctx& a, float* X, bf16_t* FA, const float* gpost, float scale, const float* gpre) {
;     ...
;     if (gw < T) {
; #pragma unroll
;         for (int j = 0; j < 4; ++j) { fn[j] = *(const u32x2*)(FA + (size_t)gw * 1024 + 4 * lane + 256 * j); xn[j] = __builtin_nontemporal_load((const f32x4*)(X + (size_t)gw * 1024 + 4 * lane + 256 * j)); }
;     }
;     for (int row = gw; row < T; row += NGW) {
;         float* xr = X + (size_t)row * 1024; bf16_t* fr = FA + (size_t)row * 1024;
;         f32x4 f[4], x[4]; float ss = 0.f;
; #pragma unroll
;         for (int j = 0; j < 4; ++j) { f[j] = (f32x4){bflo(fn[j].x), bfhi(fn[j].x), bflo(fn[j].y), bfhi(fn[j].y)}; x[j] = xn[j];
;             ss += f[j][0] * f[j][0] + f[j][1] * f[j][1] + f[j][2] * f[j][2] + f[j][3] * f[j][3]; }
;         const int nrow = row + NGW;
;         if (nrow < T) {
; #pragma unroll
;             for (int j = 0; j < 4; ++j) { fn[j] = *(const u32x2*)(FA + (size_t)nrow * 1024 + 4 * lane + 256 * j); xn[j] = __builtin_nontemporal_load((const f32x4*)(X + (size_t)nrow * 1024 + 4 * lane + 256 * j)); }
;         }
.LBB0_677:
	v_ashrrev_i32_e32 v34, 6, v183
	v_readlane_b32 s2, v245, 10
	s_nop 1
	v_add_u32_e32 v66, s2, v34
	v_cmp_gt_i32_e32 vcc, s91, v66
	s_and_saveexec_b64 s[2:3], vcc
	s_cbranch_execz .LBB0_684
	v_ashrrev_i32_e32 v67, 31, v66
	v_readlane_b32 s6, v244, 15
	v_lshlrev_b64 v[38:39], 11, v[66:67]
	v_readlane_b32 s7, v244, 16
	v_lshlrev_b32_e32 v36, 1, v36
	v_mov_b32_e32 v37, v1
	v_lshl_add_u64 v[40:41], s[6:7], 0, v[38:39]
	v_lshl_add_u64 v[36:37], v[40:41], 0, v[36:37]
	v_lshlrev_b64 v[40:41], 12, v[66:67]
	v_lshl_add_u64 v[68:69], s[28:29], 0, v[40:41]
	v_lshl_add_u64 v[40:41], v[68:69], 0, v[0:1]
	global_load_dwordx4 v[62:65], v[40:41], off nt
	global_load_dwordx4 v[58:61], v[40:41], off offset:1024 nt
	global_load_dwordx4 v[54:57], v[40:41], off offset:2048 nt
	global_load_dwordx4 v[50:53], v[40:41], off offset:3072 nt
	global_load_dwordx2 v[92:93], v[36:37], off
	global_load_dwordx2 v[90:91], v[36:37], off offset:512
	global_load_dwordx2 v[88:89], v[36:37], off offset:1024
	global_load_dwordx2 v[86:87], v[36:37], off offset:1536
	v_and_b32_e32 v0, 64, v169
	v_readlane_b32 s6, v245, 11
	v_xor_b32_e32 v40, 1, v169
	v_add_u32_e32 v0, 64, v0
	v_add_u32_e32 v34, s6, v34
	v_readlane_b32 s6, v244, 17
	v_xor_b32_e32 v41, 2, v169
	v_readlane_b32 s7, v244, 18
	v_cmp_lt_i32_e32 vcc, v40, v0
	v_xor_b32_e32 v42, 4, v169
	v_lshl_add_u64 v[72:73], s[6:7], 0, v[38:39]
	v_cndmask_b32_e32 v38, v169, v40, vcc
	v_cmp_lt_i32_e32 vcc, v41, v0
	v_xor_b32_e32 v43, 8, v169
	v_xor_b32_e32 v44, 16, v169
	v_cndmask_b32_e32 v39, v169, v41, vcc
	v_cmp_lt_i32_e32 vcc, v42, v0
	v_xor_b32_e32 v45, 32, v169
	v_ashrrev_i32_e32 v35, 31, v34
	v_cndmask_b32_e32 v40, v169, v42, vcc
	v_cmp_lt_i32_e32 vcc, v43, v0
	v_and_b32_e32 v46, 63, v183
	v_lshlrev_b64 v[36:37], 11, v[34:35]
	v_cndmask_b32_e32 v41, v169, v43, vcc
	v_cmp_lt_i32_e32 vcc, v44, v0
	v_lshlrev_b64 v[34:35], 12, v[34:35]
	v_lshlrev_b32_e32 v70, 4, v46
	v_cndmask_b32_e32 v42, v169, v44, vcc
	v_cmp_lt_i32_e32 vcc, v45, v0
	v_lshlrev_b32_e32 v0, 3, v46
	v_lshl_add_u64 v[74:75], s[6:7], 0, v[36:37]
	v_cndmask_b32_e32 v43, v169, v45, vcc
	v_lshl_add_u64 v[76:77], s[28:29], 0, v[34:35]
	v_lshlrev_b32_e32 v94, 2, v38
	v_lshlrev_b32_e32 v95, 2, v39
	v_lshlrev_b32_e32 v96, 2, v40
	v_lshlrev_b32_e32 v97, 2, v41
	v_lshlrev_b32_e32 v98, 2, v42
	v_lshlrev_b32_e32 v99, 2, v43
	v_cndmask_b32_e64 v67, 0.5, 1.0, s[14:15]
	v_mov_b32_e32 v71, v1
	s_mov_b64 s[14:15], 0
	s_waitcnt vmcnt(0)
	v_mov_b64_e32 v[34:35], v[62:63]
	v_mov_b64_e32 v[38:39], v[58:59]
	v_mov_b64_e32 v[42:43], v[54:55]
	v_mov_b64_e32 v[46:47], v[50:51]
	v_mov_b64_e32 v[36:37], v[64:65]
	v_mov_b64_e32 v[40:41], v[60:61]
	v_mov_b64_e32 v[44:45], v[56:57]
	v_mov_b64_e32 v[48:49], v[52:53]
	v_readfirstlane_b32 s42, v66
	v_readlane_b32 s20, v244, 15
	v_readlane_b32 s43, v244, 16
	s_lshl_b32 s6, s42, 12
	s_add_u32 s98, s28, s6
	s_addc_u32 s99, s29, 0
	s_lshl_b32 s6, s42, 11
	s_add_u32 s100, s20, s6
	s_addc_u32 s101, s43, 0
	s_add_u32 s6, s98, s24
	s_addc_u32 s7, s99, s25
	v_readlane_b32 s20, v245, 58
	v_readlane_b32 s43, v245, 59
	s_nop 0
	s_add_u32 s14, s100, s20
	s_addc_u32 s15, s101, s43
	s_lshl_b32 s16, s24, 1
	s_lshl_b32 s17, s20, 1
	s_add_i32 s20, s42, s8
	s_cmp_lt_u32 s20, s91
	s_cbranch_scc0 .Lep_loop
	global_load_dwordx4 v[124:127], v70, s[6:7] nt
	global_load_dwordx4 v[120:123], v70, s[6:7] offset:1024 nt
	global_load_dwordx4 v[116:119], v70, s[6:7] offset:2048 nt
	global_load_dwordx4 v[112:115], v70, s[6:7] offset:3072 nt
	global_load_dwordx2 v[134:135], v0, s[14:15]
	global_load_dwordx2 v[132:133], v0, s[14:15] offset:512
	global_load_dwordx2 v[130:131], v0, s[14:15] offset:1024
	global_load_dwordx2 v[128:129], v0, s[14:15] offset:1536
.Lep_loop:
	s_add_i32 s20, s42, s8
	s_cmp_lt_u32 s20, s91
	s_cbranch_scc1 .Lep_A_w
	s_waitcnt vmcnt(0)
	s_branch .Lep_A_go
.Lep_A_w:
	s_waitcnt vmcnt(12)
; __device__ __forceinline__ unsigned cvt_pk_bf16(float lo, float hi) { const f32x2_t v = {lo, hi}; const bf16x2_t b = __builtin_convertvector(v, bf16x2_t); return __builtin_bit_cast(unsigned, b); }
; __device__ __forceinline__ float bflo(unsigned w) { return __uint_as_float(w << 16); }
; __device__ __forceinline__ float bfhi(unsigned w) { return __uint_as_float(w & 0xffff0000u); }
; __device__ __forceinline__ void e_phase(const Ctx& a, float* X, bf16_t* FA, const float* gpost, float scale, const float* gpre) {
;     ...
;         float* xr = X + (size_t)row * 1024; bf16_t* fr = FA + (size_t)row * 1024;
;         f32x4 f[4], x[4]; float ss = 0.f;
; #pragma unroll
;         for (int j = 0; j < 4; ++j) { f[j] = (f32x4){bflo(fn[j].x), bfhi(fn[j].x), bflo(fn[j].y), bfhi(fn[j].y)}; x[j] = xn[j];
;             ss += f[j][0] * f[j][0] + f[j][1] * f[j][1] + f[j][2] * f[j][2] + f[j][3] * f[j][3]; }
;         const int nrow = row + NGW;
;         if (nrow < T) {
; #pragma unroll
;             for (int j = 0; j < 4; ++j) { fn[j] = *(const u32x2*)(FA + (size_t)nrow * 1024 + 4 * lane + 256 * j); xn[j] = __builtin_nontemporal_load((const f32x4*)(X + (size_t)nrow * 1024 + 4 * lane + 256 * j)); }
;         }
;         const float rs = rsqrtf(wave_sum(ss) * (1.f / 1024.f) + EPS) * scale;
;         float s2 = 0.f;
; #pragma unroll
;         for (int j = 0; j < 4; ++j) { const f32x4 g = gp[j];
;             x[j] = x[j] + f[j] * g * rs; __builtin_nontemporal_store(x[j], (f32x4*)(xr + 4 * lane + 256 * j));
;             s2 += x[j][0] * x[j][0] + x[j][1] * x[j][1] + x[j][2] * x[j][2] + x[j][3] * x[j][3]; }
;         if (gpre) {
;             const float r2 = rsqrtf(wave_sum(s2) * (1.f / 1024.f) + EPS);
; #pragma unroll
;             for (int j = 0; j < 4; ++j) { const f32x4 g = gq[j];
;                 u32x2 w; w.x = cvt_pk_bf16(x[j][0] * r2 * g[0], x[j][1] * r2 * g[1]); w.y = cvt_pk_bf16(x[j][2] * r2 * g[2], x[j][3] * r2 * g[3]);
;                 *(u32x2*)(fr + 4 * lane + 256 * j) = w; }
;         }
;     }
.Lep_A_go:
	v_and_b32_e32 v101, 0xffff0000, v92
	v_and_b32_e32 v103, 0xffff0000, v90
	v_lshlrev_b32_e32 v100, 16, v92
	v_mul_f32_e32 v104, v101, v101
	v_lshlrev_b32_e32 v102, 16, v90
	v_mul_f32_e32 v105, v103, v103
	v_lshlrev_b32_e32 v92, 16, v93
	v_fmac_f32_e32 v104, v100, v100
	v_lshlrev_b32_e32 v90, 16, v91
	v_fmac_f32_e32 v105, v102, v102
	v_and_b32_e32 v93, 0xffff0000, v93
	v_fmac_f32_e32 v104, v92, v92
	v_and_b32_e32 v91, 0xffff0000, v91
	v_fmac_f32_e32 v105, v90, v90
	v_fmac_f32_e32 v104, v93, v93
	v_fmac_f32_e32 v105, v91, v91
	v_add_f32_e32 v106, v104, v105
	v_and_b32_e32 v105, 0xffff0000, v88
	v_lshlrev_b32_e32 v104, 16, v88
	v_mul_f32_e32 v107, v105, v105
	v_lshlrev_b32_e32 v88, 16, v89
	v_fmac_f32_e32 v107, v104, v104
	v_and_b32_e32 v89, 0xffff0000, v89
	v_fmac_f32_e32 v107, v88, v88
	v_fmac_f32_e32 v107, v89, v89
	v_add_f32_e32 v108, v107, v106
	v_and_b32_e32 v107, 0xffff0000, v86
	v_lshlrev_b32_e32 v106, 16, v86
	v_mul_f32_e32 v109, v107, v107
	v_lshlrev_b32_e32 v86, 16, v87
	v_fmac_f32_e32 v109, v106, v106
	v_and_b32_e32 v87, 0xffff0000, v87
	v_fmac_f32_e32 v109, v86, v86
	v_fmac_f32_e32 v109, v87, v87
	v_add_f32_e32 v108, v109, v108
	ds_bpermute_b32 v109, v94, v108
	v_pk_mul_f32 v[92:93], v[4:5], v[92:93]
	v_pk_mul_f32 v[90:91], v[16:17], v[90:91]
	v_pk_mul_f32 v[88:89], v[20:21], v[88:89]
	v_pk_mul_f32 v[100:101], v[2:3], v[100:101]
	s_waitcnt lgkmcnt(0)
	v_add_f32_e32 v108, v108, v109
	ds_bpermute_b32 v109, v95, v108
	v_pk_mul_f32 v[86:87], v[32:33], v[86:87]
	s_waitcnt lgkmcnt(0)
	v_add_f32_e32 v108, v108, v109
	ds_bpermute_b32 v109, v96, v108
	s_waitcnt lgkmcnt(0)
	v_add_f32_e32 v108, v108, v109
	ds_bpermute_b32 v109, v97, v108
	s_waitcnt lgkmcnt(0)
	v_add_f32_e32 v108, v108, v109
	ds_bpermute_b32 v109, v98, v108
	s_waitcnt lgkmcnt(0)
	v_add_f32_e32 v108, v108, v109
	ds_bpermute_b32 v109, v99, v108
	s_waitcnt lgkmcnt(0)
	v_add_f32_e32 v108, v108, v109
	v_fmamk_f32 v108, v108, 0x3a800000, v170
	v_mul_f32_e32 v109, 0x4b800000, v108
	v_cmp_gt_f32_e32 vcc, s97, v108
	s_nop 1
	v_cndmask_b32_e32 v108, v108, v109, vcc
	v_rsq_f32_e32 v108, v108
	s_nop 0
	v_mul_f32_e32 v109, 0x45800000, v108
	v_cndmask_b32_e32 v108, v108, v109, vcc
	v_mul_f32_e32 v108, v67, v108
	v_pk_fma_f32 v[64:65], v[92:93], v[108:109], v[64:65] op_sel_hi:[1,0,1]
	v_pk_mul_f32 v[92:93], v[14:15], v[102:103]
	v_pk_fma_f32 v[60:61], v[90:91], v[108:109], v[60:61] op_sel_hi:[1,0,1]
	v_pk_mul_f32 v[90:91], v[18:19], v[104:105]
	v_pk_fma_f32 v[56:57], v[88:89], v[108:109], v[56:57] op_sel_hi:[1,0,1]
	v_pk_mul_f32 v[88:89], v[30:31], v[106:107]
	v_pk_fma_f32 v[62:63], v[100:101], v[108:109], v[62:63] op_sel_hi:[1,0,1]
	v_pk_fma_f32 v[58:59], v[92:93], v[108:109], v[58:59] op_sel_hi:[1,0,1]
	v_pk_fma_f32 v[54:55], v[90:91], v[108:109], v[54:55] op_sel_hi:[1,0,1]
	v_pk_fma_f32 v[52:53], v[86:87], v[108:109], v[52:53] op_sel_hi:[1,0,1]
	v_pk_fma_f32 v[50:51], v[88:89], v[108:109], v[50:51] op_sel_hi:[1,0,1]
	s_and_b64 vcc, exec, s[40:41]
	global_store_dwordx4 v70, v[62:65], s[98:99] nt
	global_store_dwordx4 v70, v[58:61], s[98:99] offset:1024 nt
	global_store_dwordx4 v70, v[54:57], s[98:99] offset:2048 nt
	global_store_dwordx4 v70, v[50:53], s[98:99] offset:3072 nt
	s_cbranch_vccnz .Lep_A_noh
	v_mov_b32_e32 v92, v63
	v_mov_b32_e32 v93, v59
	v_mov_b32_e32 v90, v62
	v_mov_b32_e32 v91, v58
	v_pk_mul_f32 v[92:93], v[92:93], v[92:93]
	v_mov_b32_e32 v100, v51
	v_mov_b32_e32 v101, v55
	v_mov_b32_e32 v88, v64
	v_mov_b32_e32 v89, v60
	v_pk_fma_f32 v[90:91], v[90:91], v[90:91], v[92:93]
	v_mov_b32_e32 v92, v50
	v_mov_b32_e32 v93, v54
	v_pk_mul_f32 v[100:101], v[100:101], v[100:101]
	v_mov_b32_e32 v86, v65
	v_mov_b32_e32 v87, v61
	v_pk_fma_f32 v[88:89], v[88:89], v[88:89], v[90:91]
	v_mov_b32_e32 v90, v52
	v_mov_b32_e32 v91, v56
	v_pk_fma_f32 v[92:93], v[92:93], v[92:93], v[100:101]
	v_pk_fma_f32 v[86:87], v[86:87], v[86:87], v[88:89]
	v_mov_b32_e32 v88, v53
	v_mov_b32_e32 v89, v57
	v_pk_fma_f32 v[90:91], v[90:91], v[90:91], v[92:93]
	v_add_f32_e32 v86, v86, v87
	v_pk_fma_f32 v[88:89], v[88:89], v[88:89], v[90:91]
	v_add_f32_e32 v86, v89, v86
	v_add_f32_e32 v86, v88, v86
	ds_bpermute_b32 v87, v94, v86
	s_waitcnt lgkmcnt(0)
	v_add_f32_e32 v86, v86, v87
	ds_bpermute_b32 v87, v95, v86
	s_waitcnt lgkmcnt(0)
	v_add_f32_e32 v86, v86, v87
	ds_bpermute_b32 v87, v96, v86
	s_waitcnt lgkmcnt(0)
	v_add_f32_e32 v86, v86, v87
	ds_bpermute_b32 v87, v97, v86
	s_waitcnt lgkmcnt(0)
	v_add_f32_e32 v86, v86, v87
	ds_bpermute_b32 v87, v98, v86
	s_waitcnt lgkmcnt(0)
	v_add_f32_e32 v86, v86, v87
	ds_bpermute_b32 v87, v99, v86
	s_waitcnt lgkmcnt(0)
	v_add_f32_e32 v86, v86, v87
	v_fmamk_f32 v86, v86, 0x3a800000, v170
	v_mul_f32_e32 v87, 0x4b800000, v86
	v_cmp_gt_f32_e32 vcc, s97, v86
	s_nop 1
	v_cndmask_b32_e32 v86, v86, v87, vcc
	v_rsq_f32_e32 v88, v86
	v_mul_f32_e32 v89, 0x45800000, v88
	v_cndmask_b32_e32 v88, v88, v89, vcc
	v_pk_mul_f32 v[62:63], v[62:63], v[88:89] op_sel_hi:[1,0]
	v_pk_mul_f32 v[64:65], v[64:65], v[88:89] op_sel_hi:[1,0]
	v_pk_mul_f32 v[62:63], v[10:11], v[62:63]
	v_pk_mul_f32 v[64:65], v[12:13], v[64:65]
	v_pk_mul_f32 v[58:59], v[58:59], v[88:89] op_sel_hi:[1,0]
	v_pk_mul_f32 v[60:61], v[60:61], v[88:89] op_sel_hi:[1,0]
	v_pk_mul_f32 v[54:55], v[54:55], v[88:89] op_sel_hi:[1,0]
	v_pk_mul_f32 v[56:57], v[56:57], v[88:89] op_sel_hi:[1,0]
	v_pk_mul_f32 v[50:51], v[50:51], v[88:89] op_sel_hi:[1,0]
	v_pk_mul_f32 v[52:53], v[52:53], v[88:89] op_sel_hi:[1,0]
	v_cvt_pk_bf16_f32 v62, v62, v63
	v_cvt_pk_bf16_f32 v63, v64, v65
	v_pk_mul_f32 v[58:59], v[6:7], v[58:59]
	v_pk_mul_f32 v[60:61], v[8:9], v[60:61]
	v_pk_mul_f32 v[54:55], v[26:27], v[54:55]
	v_pk_mul_f32 v[56:57], v[28:29], v[56:57]
	v_pk_mul_f32 v[50:51], v[22:23], v[50:51]
	v_pk_mul_f32 v[52:53], v[24:25], v[52:53]
	v_cvt_pk_bf16_f32 v58, v58, v59
	v_cvt_pk_bf16_f32 v59, v60, v61
	v_cvt_pk_bf16_f32 v54, v54, v55
	v_cvt_pk_bf16_f32 v55, v56, v57
	v_cvt_pk_bf16_f32 v50, v50, v51
	v_cvt_pk_bf16_f32 v51, v52, v53
	global_store_dwordx2 v0, v[62:63], s[100:101]
	global_store_dwordx2 v0, v[58:59], s[100:101] offset:512
	global_store_dwordx2 v0, v[54:55], s[100:101] offset:1024
	global_store_dwordx2 v0, v[50:51], s[100:101] offset:1536
.Lep_A_noh:
	s_lshl_b32 s20, s8, 1
	s_add_i32 s20, s42, s20
	s_cmp_lt_u32 s20, s91
	s_cbranch_scc0 .Lep_A_nore
	s_add_u32 s98, s98, s16
	s_addc_u32 s99, s99, 0
	s_add_u32 s100, s100, s17
	s_addc_u32 s101, s101, 0
	global_load_dwordx4 v[62:65], v70, s[98:99] nt
	global_load_dwordx4 v[58:61], v70, s[98:99] offset:1024 nt
	global_load_dwordx4 v[54:57], v70, s[98:99] offset:2048 nt
	global_load_dwordx4 v[50:53], v70, s[98:99] offset:3072 nt
	global_load_dwordx2 v[92:93], v0, s[100:101]
	global_load_dwordx2 v[90:91], v0, s[100:101] offset:512
	global_load_dwordx2 v[88:89], v0, s[100:101] offset:1024
	global_load_dwordx2 v[86:87], v0, s[100:101] offset:1536
.Lep_A_nore:
	s_add_i32 s20, s42, s8
	s_cmp_lt_u32 s20, s91
	s_cbranch_scc0 .Lep_done
	s_lshl_b32 s20, s8, 1
	s_add_i32 s20, s42, s20
	s_cmp_lt_u32 s20, s91
	s_cbranch_scc1 .Lep_B_w
	s_waitcnt vmcnt(0)
	s_branch .Lep_B_go

; __device__ __forceinline__ unsigned cvt_pk_bf16(float lo, float hi) { const f32x2_t v = {lo, hi}; const bf16x2_t b = __builtin_convertvector(v, bf16x2_t); return __builtin_bit_cast(unsigned, b); }
; __device__ __forceinline__ float bflo(unsigned w) { return __uint_as_float(w << 16); }
; __device__ __forceinline__ float bfhi(unsigned w) { return __uint_as_float(w & 0xffff0000u); }
; __device__ __forceinline__ void e_phase(const Ctx& a, float* X, bf16_t* FA, const float* gpost, float scale, const float* gpre) {
;     ...
;         float* xr = X + (size_t)row * 1024; bf16_t* fr = FA + (size_t)row * 1024;
;         f32x4 f[4], x[4]; float ss = 0.f;
; #pragma unroll
;         for (int j = 0; j < 4; ++j) { f[j] = (f32x4){bflo(fn[j].x), bfhi(fn[j].x), bflo(fn[j].y), bfhi(fn[j].y)}; x[j] = xn[j];
;             ss += f[j][0] * f[j][0] + f[j][1] * f[j][1] + f[j][2] * f[j][2] + f[j][3] * f[j][3]; }
;         const int nrow = row + NGW;
;         if (nrow < T) {
; #pragma unroll
;             for (int j = 0; j < 4; ++j) { fn[j] = *(const u32x2*)(FA + (size_t)nrow * 1024 + 4 * lane + 256 * j); xn[j] = __builtin_nontemporal_load((const f32x4*)(X + (size_t)nrow * 1024 + 4 * lane + 256 * j)); }
;         }
;         const float rs = rsqrtf(wave_sum(ss) * (1.f / 1024.f) + EPS) * scale;
;         float s2 = 0.f;
; #pragma unroll
;         for (int j = 0; j < 4; ++j) { const f32x4 g = gp[j];
;             x[j] = x[j] + f[j] * g * rs; __builtin_nontemporal_store(x[j], (f32x4*)(xr + 4 * lane + 256 * j));
;             s2 += x[j][0] * x[j][0] + x[j][1] * x[j][1] + x[j][2] * x[j][2] + x[j][3] * x[j][3]; }
;         if (gpre) {
;             const float r2 = rsqrtf(wave_sum(s2) * (1.f / 1024.f) + EPS);
; #pragma unroll
;             for (int j = 0; j < 4; ++j) { const f32x4 g = gq[j];
;                 u32x2 w; w.x = cvt_pk_bf16(x[j][0] * r2 * g[0], x[j][1] * r2 * g[1]); w.y = cvt_pk_bf16(x[j][2] * r2 * g[2], x[j][3] * r2 * g[3]);
;                 *(u32x2*)(fr + 4 * lane + 256 * j) = w; }
.Lep_B_go:
	v_and_b32_e32 v101, 0xffff0000, v134
	v_and_b32_e32 v103, 0xffff0000, v132
	v_lshlrev_b32_e32 v100, 16, v134
	v_mul_f32_e32 v104, v101, v101
	v_lshlrev_b32_e32 v102, 16, v132
	v_mul_f32_e32 v105, v103, v103
	v_lshlrev_b32_e32 v134, 16, v135
	v_fmac_f32_e32 v104, v100, v100
	v_lshlrev_b32_e32 v132, 16, v133
	v_fmac_f32_e32 v105, v102, v102
	v_and_b32_e32 v135, 0xffff0000, v135
	v_fmac_f32_e32 v104, v134, v134
	v_and_b32_e32 v133, 0xffff0000, v133
	v_fmac_f32_e32 v105, v132, v132
	v_fmac_f32_e32 v104, v135, v135
	v_fmac_f32_e32 v105, v133, v133
	v_add_f32_e32 v106, v104, v105
	v_and_b32_e32 v105, 0xffff0000, v130
	v_lshlrev_b32_e32 v104, 16, v130
	v_mul_f32_e32 v107, v105, v105
	v_lshlrev_b32_e32 v130, 16, v131
	v_fmac_f32_e32 v107, v104, v104
	v_and_b32_e32 v131, 0xffff0000, v131
	v_fmac_f32_e32 v107, v130, v130
	v_fmac_f32_e32 v107, v131, v131
	v_add_f32_e32 v108, v107, v106
	v_and_b32_e32 v107, 0xffff0000, v128
	v_lshlrev_b32_e32 v106, 16, v128
	v_mul_f32_e32 v109, v107, v107
	v_lshlrev_b32_e32 v128, 16, v129
	v_fmac_f32_e32 v109, v106, v106
	v_and_b32_e32 v129, 0xffff0000, v129
	v_fmac_f32_e32 v109, v128, v128
	v_fmac_f32_e32 v109, v129, v129
	v_add_f32_e32 v108, v109, v108
	ds_bpermute_b32 v109, v94, v108
	v_pk_mul_f32 v[134:135], v[4:5], v[134:135]
	v_pk_mul_f32 v[132:133], v[16:17], v[132:133]
	v_pk_mul_f32 v[130:131], v[20:21], v[130:131]
	v_pk_mul_f32 v[100:101], v[2:3], v[100:101]
	s_waitcnt lgkmcnt(0)
	v_add_f32_e32 v108, v108, v109
	ds_bpermute_b32 v109, v95, v108
	v_pk_mul_f32 v[128:129], v[32:33], v[128:129]
	s_waitcnt lgkmcnt(0)
	v_add_f32_e32 v108, v108, v109
	ds_bpermute_b32 v109, v96, v108
	s_waitcnt lgkmcnt(0)
	v_add_f32_e32 v108, v108, v109
	ds_bpermute_b32 v109, v97, v108
	s_waitcnt lgkmcnt(0)
	v_add_f32_e32 v108, v108, v109
	ds_bpermute_b32 v109, v98, v108
	s_waitcnt lgkmcnt(0)
	v_add_f32_e32 v108, v108, v109
	ds_bpermute_b32 v109, v99, v108
	s_waitcnt lgkmcnt(0)
	v_add_f32_e32 v108, v108, v109
	v_fmamk_f32 v108, v108, 0x3a800000, v170
	v_mul_f32_e32 v109, 0x4b800000, v108
	v_cmp_gt_f32_e32 vcc, s97, v108
	s_nop 1
	v_cndmask_b32_e32 v108, v108, v109, vcc
	v_rsq_f32_e32 v108, v108
	s_nop 0
	v_mul_f32_e32 v109, 0x45800000, v108
	v_cndmask_b32_e32 v108, v108, v109, vcc
	v_mul_f32_e32 v108, v67, v108
	v_pk_fma_f32 v[126:127], v[134:135], v[108:109], v[126:127] op_sel_hi:[1,0,1]
	v_pk_mul_f32 v[134:135], v[14:15], v[102:103]
	v_pk_fma_f32 v[122:123], v[132:133], v[108:109], v[122:123] op_sel_hi:[1,0,1]
	v_pk_mul_f32 v[132:133], v[18:19], v[104:105]
	v_pk_fma_f32 v[118:119], v[130:131], v[108:109], v[118:119] op_sel_hi:[1,0,1]
	v_pk_mul_f32 v[130:131], v[30:31], v[106:107]
	v_pk_fma_f32 v[124:125], v[100:101], v[108:109], v[124:125] op_sel_hi:[1,0,1]
	v_pk_fma_f32 v[120:121], v[134:135], v[108:109], v[120:121] op_sel_hi:[1,0,1]
	v_pk_fma_f32 v[116:117], v[132:133], v[108:109], v[116:117] op_sel_hi:[1,0,1]
	v_pk_fma_f32 v[114:115], v[128:129], v[108:109], v[114:115] op_sel_hi:[1,0,1]
	v_pk_fma_f32 v[112:113], v[130:131], v[108:109], v[112:113] op_sel_hi:[1,0,1]
	s_and_b64 vcc, exec, s[40:41]
	global_store_dwordx4 v70, v[124:127], s[6:7] nt
	global_store_dwordx4 v70, v[120:123], s[6:7] offset:1024 nt
	global_store_dwordx4 v70, v[116:119], s[6:7] offset:2048 nt
	global_store_dwordx4 v70, v[112:115], s[6:7] offset:3072 nt
	s_cbranch_vccnz .Lep_B_noh
	v_mov_b32_e32 v134, v125
	v_mov_b32_e32 v135, v121
	v_mov_b32_e32 v132, v124
	v_mov_b32_e32 v133, v120
	v_pk_mul_f32 v[134:135], v[134:135], v[134:135]
	v_mov_b32_e32 v100, v113
	v_mov_b32_e32 v101, v117
	v_mov_b32_e32 v130, v126
	v_mov_b32_e32 v131, v122
	v_pk_fma_f32 v[132:133], v[132:133], v[132:133], v[134:135]
	v_mov_b32_e32 v134, v112
	v_mov_b32_e32 v135, v116
	v_pk_mul_f32 v[100:101], v[100:101], v[100:101]
	v_mov_b32_e32 v128, v127
	v_mov_b32_e32 v129, v123
	v_pk_fma_f32 v[130:131], v[130:131], v[130:131], v[132:133]
	v_mov_b32_e32 v132, v114
	v_mov_b32_e32 v133, v118
	v_pk_fma_f32 v[134:135], v[134:135], v[134:135], v[100:101]
	v_pk_fma_f32 v[128:129], v[128:129], v[128:129], v[130:131]
	v_mov_b32_e32 v130, v115
	v_mov_b32_e32 v131, v119
	v_pk_fma_f32 v[132:133], v[132:133], v[132:133], v[134:135]
	v_add_f32_e32 v128, v128, v129
	v_pk_fma_f32 v[130:131], v[130:131], v[130:131], v[132:133]
	v_add_f32_e32 v128, v131, v128
	v_add_f32_e32 v128, v130, v128
	ds_bpermute_b32 v129, v94, v128
	s_waitcnt lgkmcnt(0)
	v_add_f32_e32 v128, v128, v129
	ds_bpermute_b32 v129, v95, v128
	s_waitcnt lgkmcnt(0)
	v_add_f32_e32 v128, v128, v129
	ds_bpermute_b32 v129, v96, v128
	s_waitcnt lgkmcnt(0)
	v_add_f32_e32 v128, v128, v129
	ds_bpermute_b32 v129, v97, v128
	s_waitcnt lgkmcnt(0)
	v_add_f32_e32 v128, v128, v129
	ds_bpermute_b32 v129, v98, v128
	s_waitcnt lgkmcnt(0)
	v_add_f32_e32 v128, v128, v129
	ds_bpermute_b32 v129, v99, v128
	s_waitcnt lgkmcnt(0)
	v_add_f32_e32 v128, v128, v129
	v_fmamk_f32 v128, v128, 0x3a800000, v170
	v_mul_f32_e32 v129, 0x4b800000, v128
	v_cmp_gt_f32_e32 vcc, s97, v128
	s_nop 1
	v_cndmask_b32_e32 v128, v128, v129, vcc
	v_rsq_f32_e32 v130, v128
	v_mul_f32_e32 v131, 0x45800000, v130
	v_cndmask_b32_e32 v130, v130, v131, vcc
	v_pk_mul_f32 v[124:125], v[124:125], v[130:131] op_sel_hi:[1,0]
	v_pk_mul_f32 v[126:127], v[126:127], v[130:131] op_sel_hi:[1,0]
	v_pk_mul_f32 v[124:125], v[10:11], v[124:125]
	v_pk_mul_f32 v[126:127], v[12:13], v[126:127]
	v_pk_mul_f32 v[120:121], v[120:121], v[130:131] op_sel_hi:[1,0]
	v_pk_mul_f32 v[122:123], v[122:123], v[130:131] op_sel_hi:[1,0]
	v_pk_mul_f32 v[116:117], v[116:117], v[130:131] op_sel_hi:[1,0]
	v_pk_mul_f32 v[118:119], v[118:119], v[130:131] op_sel_hi:[1,0]
	v_pk_mul_f32 v[112:113], v[112:113], v[130:131] op_sel_hi:[1,0]
	v_pk_mul_f32 v[114:115], v[114:115], v[130:131] op_sel_hi:[1,0]
	v_cvt_pk_bf16_f32 v124, v124, v125
	v_cvt_pk_bf16_f32 v125, v126, v127
	v_pk_mul_f32 v[120:121], v[6:7], v[120:121]
	v_pk_mul_f32 v[122:123], v[8:9], v[122:123]
	v_pk_mul_f32 v[116:117], v[26:27], v[116:117]
	v_pk_mul_f32 v[118:119], v[28:29], v[118:119]
	v_pk_mul_f32 v[112:113], v[22:23], v[112:113]
	v_pk_mul_f32 v[114:115], v[24:25], v[114:115]
	v_cvt_pk_bf16_f32 v120, v120, v121
	v_cvt_pk_bf16_f32 v121, v122, v123
	v_cvt_pk_bf16_f32 v116, v116, v117
	v_cvt_pk_bf16_f32 v117, v118, v119
	v_cvt_pk_bf16_f32 v112, v112, v113
	v_cvt_pk_bf16_f32 v113, v114, v115
	global_store_dwordx2 v0, v[124:125], s[14:15]
	global_store_dwordx2 v0, v[120:121], s[14:15] offset:512
	global_store_dwordx2 v0, v[116:117], s[14:15] offset:1024
	global_store_dwordx2 v0, v[112:113], s[14:15] offset:1536
; __device__ __forceinline__ float bflo(unsigned w) { return __uint_as_float(w << 16); }
; __device__ __forceinline__ float bfhi(unsigned w) { return __uint_as_float(w & 0xffff0000u); }
; __device__ __forceinline__ void e_phase(const Ctx& a, float* X, bf16_t* FA, const float* gpost, float scale, const float* gpre) {
;     ...
;     for (int row = gw; row < T; row += NGW) {
;         float* xr = X + (size_t)row * 1024; bf16_t* fr = FA + (size_t)row * 1024;
;         f32x4 f[4], x[4]; float ss = 0.f;
; #pragma unroll
;         for (int j = 0; j < 4; ++j) { f[j] = (f32x4){bflo(fn[j].x), bfhi(fn[j].x), bflo(fn[j].y), bfhi(fn[j].y)}; x[j] = xn[j];
;             ss += f[j][0] * f[j][0] + f[j][1] * f[j][1] + f[j][2] * f[j][2] + f[j][3] * f[j][3]; }
;         const int nrow = row + NGW;
;         if (nrow < T) {
; #pragma unroll
;             for (int j = 0; j < 4; ++j) { fn[j] = *(const u32x2*)(FA + (size_t)nrow * 1024 + 4 * lane + 256 * j); xn[j] = __builtin_nontemporal_load((const f32x4*)(X + (size_t)nrow * 1024 + 4 * lane + 256 * j)); }
;         }
.Lep_B_noh:
	s_mul_i32 s20, s8, 3
	s_add_i32 s20, s42, s20
	s_cmp_lt_u32 s20, s91
	s_cbranch_scc0 .Lep_B_nore
	s_add_u32 s6, s6, s16
	s_addc_u32 s7, s7, 0
	s_add_u32 s14, s14, s17
	s_addc_u32 s15, s15, 0
	global_load_dwordx4 v[124:127], v70, s[6:7] nt
	global_load_dwordx4 v[120:123], v70, s[6:7] offset:1024 nt
	global_load_dwordx4 v[116:119], v70, s[6:7] offset:2048 nt
	global_load_dwordx4 v[112:115], v70, s[6:7] offset:3072 nt
	global_load_dwordx2 v[134:135], v0, s[14:15]
	global_load_dwordx2 v[132:133], v0, s[14:15] offset:512
	global_load_dwordx2 v[130:131], v0, s[14:15] offset:1024
	global_load_dwordx2 v[128:129], v0, s[14:15] offset:1536
.Lep_B_nore:
	s_lshl_b32 s20, s8, 1
	s_add_i32 s42, s42, s20
	s_cmp_lt_u32 s42, s91
	s_cbranch_scc1 .Lep_loop
.Lep_done:
.LBB0_684:
	s_or_b64 exec, exec, s[2:3]
